# norm phases: prefetch gain/shift/scale vectors of chunks 1-3 with chunk 0 (were serialized behind full vmcnt drains)
# speedup vs baseline: 1.0147x; 1.0147x over previous
; DI unsigned cvt_pk_bf16(float lo, float hi) { f32x2_t v = {lo, hi}; bf16x2_t b = __builtin_convertvector(v, bf16x2_t); return __builtin_bit_cast(unsigned, b); }
; DI void phase_norm(const Params& p, int l, const float* g, int shift_idx, bool skip_ctx, bool from_input) {
;     ...
;       float ss = 0.f;
; #pragma unroll
;       for (int i = 0; i < 4; ++i) ss += v[u][i][0] * v[u][i][0] + v[u][i][1] * v[u][i][1] + v[u][i][2] * v[u][i][2] + v[u][i][3] * v[u][i][3];
;       ss = wave_sum(ss);
;       const float rs = rsqrtf(ss * (1.f / 1024.f) + EPS);
;       const float* mr = mod + (size_t)(t < CTXL ? 8 : b) * 6144 + shift_idx * 1024;
; #pragma unroll
;       for (int i = 0; i < 4; ++i) {
;         const int col = lane * 4 + i * 256;
;         const f32x4 gg = *(const f32x4*)(g + col), sh = *(const f32x4*)(mr + col), scl = *(const f32x4*)(mr + 1024 + col);
;         f32x4 y = (v[u][i] * rs) * gg;
;         y = y * (scl + 1.f) + sh;
;         u32x2 pk; pk.x = cvt_pk_bf16(y[0], y[1]); pk.y = cvt_pk_bf16(y[2], y[3]);
;         *(u32x2*)(hb + (size_t)row * 1024 + col) = pk;
.LBB0_194:
	s_or_b64 exec, exec, s[46:47]
	v_lshlrev_b32_e32 v52, 2, v38
	v_lshlrev_b32_e32 v50, 2, v40
	v_lshlrev_b32_e32 v48, 2, v42
	s_and_saveexec_b64 s[46:47], s[48:49]
	s_cbranch_execz .LBB0_196
	s_waitcnt vmcnt(0)
	v_mov_b32_e32 v56, v31
	s_waitcnt vmcnt(2)
	v_mov_b32_e32 v57, v27
	v_mov_b32_e32 v54, v30
	v_mov_b32_e32 v55, v26
	v_pk_mul_f32 v[56:57], v[56:57], v[56:57]
	s_waitcnt vmcnt(1)
	v_mov_b32_e32 v58, v23
	v_pk_fma_f32 v[54:55], v[54:55], v[54:55], v[56:57]
	v_mov_b32_e32 v56, v32
	v_mov_b32_e32 v57, v28
	v_pk_fma_f32 v[54:55], v[56:57], v[56:57], v[54:55]
	v_mov_b32_e32 v56, v33
	v_mov_b32_e32 v57, v29
	s_waitcnt vmcnt(0)
	v_mov_b32_e32 v59, v19
	v_pk_fma_f32 v[54:55], v[56:57], v[56:57], v[54:55]
	v_mov_b32_e32 v56, v22
	v_mov_b32_e32 v57, v18
	v_pk_mul_f32 v[58:59], v[58:59], v[58:59]
	v_cndmask_b32_e64 v35, v35, 8, s[40:41]
	v_pk_fma_f32 v[56:57], v[56:57], v[56:57], v[58:59]
	v_mov_b32_e32 v58, v24
	v_mov_b32_e32 v59, v20
	v_pk_fma_f32 v[56:57], v[58:59], v[58:59], v[56:57]
	v_mov_b32_e32 v58, v25
	v_mov_b32_e32 v59, v21
	v_add_f32_e32 v43, v54, v55
	v_mul_hi_i32_i24_e32 v55, 0x6000, v35
	v_mul_i32_i24_e32 v54, 0x6000, v35
	v_pk_fma_f32 v[66:67], v[58:59], v[58:59], v[56:57]
	v_lshl_add_u64 v[58:59], s[26:27], 0, v[54:55]
	s_mov_b64 s[18:19], 0x1000
	v_lshl_add_u64 v[68:69], v[58:59], 0, s[18:19]
	v_lshl_add_u64 v[70:71], v[58:59], 0, v[0:1]
	v_lshl_add_u64 v[62:63], v[68:69], 0, v[0:1]
	global_load_dwordx4 v[54:57], v[36:37], off
	global_load_dwordx4 v[58:61], v[70:71], off
	s_nop 0
	global_load_dwordx4 v[62:65], v[62:63], off
	global_load_dwordx4 v[80:83], v[36:37], off offset:1024
	v_mov_b32_e32 v53, v1
	v_lshl_add_u64 v[116:117], v[68:69], 0, v[52:53]
	global_load_dwordx4 v[84:87], v[116:117], off
	global_load_dwordx4 v[88:91], v[70:71], off offset:1024
	global_load_dwordx4 v[92:95], v[36:37], off offset:2048
	v_mov_b32_e32 v51, v1
	v_lshl_add_u64 v[118:119], v[68:69], 0, v[50:51]
	global_load_dwordx4 v[96:99], v[118:119], off
	global_load_dwordx4 v[100:103], v[70:71], off offset:2048
	global_load_dwordx4 v[104:107], v[36:37], off offset:3072
	v_mov_b32_e32 v49, v1
	v_lshl_add_u64 v[120:121], v[68:69], 0, v[48:49]
	global_load_dwordx4 v[108:111], v[120:121], off
	global_load_dwordx4 v[112:115], v[70:71], off offset:3072
	v_add_f32_e32 v43, v43, v66
	v_add_f32_e32 v35, v43, v67
	v_and_b32_e32 v43, 64, v192
	v_add_u32_e32 v43, 64, v43
	v_xor_b32_e32 v47, 32, v192
	v_cmp_lt_i32_e32 vcc, v47, v43
	v_mov_b32_e32 v53, v1
	v_mov_b32_e32 v51, v1
	v_cndmask_b32_e32 v47, v192, v47, vcc
	v_lshlrev_b32_e32 v47, 2, v47
	ds_bpermute_b32 v47, v47, v35
	v_mov_b32_e32 v49, v1
	s_waitcnt lgkmcnt(0)
	v_add_f32_e32 v35, v35, v47
	v_xor_b32_e32 v47, 16, v192
	v_cmp_lt_i32_e32 vcc, v47, v43
	s_nop 1
	v_cndmask_b32_e32 v47, v192, v47, vcc
	v_lshlrev_b32_e32 v47, 2, v47
	ds_bpermute_b32 v47, v47, v35
	s_waitcnt lgkmcnt(0)
	v_add_f32_e32 v35, v35, v47
	v_xor_b32_e32 v47, 8, v192
	v_cmp_lt_i32_e32 vcc, v47, v43
	s_nop 1
	v_cndmask_b32_e32 v47, v192, v47, vcc
	v_lshlrev_b32_e32 v47, 2, v47
	ds_bpermute_b32 v47, v47, v35
	s_waitcnt lgkmcnt(0)
	v_add_f32_e32 v35, v35, v47
	v_xor_b32_e32 v47, 4, v192
	v_cmp_lt_i32_e32 vcc, v47, v43
	s_nop 1
	v_cndmask_b32_e32 v47, v192, v47, vcc
	v_lshlrev_b32_e32 v47, 2, v47
	ds_bpermute_b32 v47, v47, v35
	s_waitcnt lgkmcnt(0)
	v_add_f32_e32 v35, v35, v47
	v_xor_b32_e32 v47, 2, v192
	v_cmp_lt_i32_e32 vcc, v47, v43
	s_nop 1
	v_cndmask_b32_e32 v47, v192, v47, vcc
	v_lshlrev_b32_e32 v47, 2, v47
	ds_bpermute_b32 v47, v47, v35
	s_waitcnt lgkmcnt(0)
	v_add_f32_e32 v35, v35, v47
	v_xor_b32_e32 v47, 1, v192
	v_cmp_lt_i32_e32 vcc, v47, v43
	s_nop 1
	v_cndmask_b32_e32 v43, v192, v47, vcc
	v_lshlrev_b32_e32 v43, 2, v43
	ds_bpermute_b32 v43, v43, v35
	s_waitcnt lgkmcnt(0)
	v_add_f32_e32 v35, v35, v43
	v_fmamk_f32 v35, v35, 0x3a800000, v148
	v_mul_f32_e32 v43, 0x4b800000, v35
	v_cmp_gt_f32_e32 vcc, s2, v35
	s_nop 1
	v_cndmask_b32_e32 v35, v35, v43, vcc
	v_rsq_f32_e32 v35, v35
	s_nop 0
	v_mul_f32_e32 v43, 0x45800000, v35
	v_cndmask_b32_e32 v66, v35, v43, vcc
	v_pk_mul_f32 v[32:33], v[32:33], v[66:67] op_sel_hi:[1,0]
	v_pk_mul_f32 v[30:31], v[30:31], v[66:67] op_sel_hi:[1,0]
	v_ashrrev_i32_e32 v35, 31, v34
	s_waitcnt vmcnt(2)
	v_pk_mul_f32 v[30:31], v[54:55], v[30:31]
	v_pk_mul_f32 v[32:33], v[56:57], v[32:33]
	s_waitcnt vmcnt(0)
; DI unsigned cvt_pk_bf16(float lo, float hi) { f32x2_t v = {lo, hi}; bf16x2_t b = __builtin_convertvector(v, bf16x2_t); return __builtin_bit_cast(unsigned, b); }
; DI void phase_norm(const Params& p, int l, const float* g, int shift_idx, bool skip_ctx, bool from_input) {
;     ...
;       const float rs = rsqrtf(ss * (1.f / 1024.f) + EPS);
;       const float* mr = mod + (size_t)(t < CTXL ? 8 : b) * 6144 + shift_idx * 1024;
; #pragma unroll
;       for (int i = 0; i < 4; ++i) {
;         const int col = lane * 4 + i * 256;
;         const f32x4 gg = *(const f32x4*)(g + col), sh = *(const f32x4*)(mr + col), scl = *(const f32x4*)(mr + 1024 + col);
;         f32x4 y = (v[u][i] * rs) * gg;
;         y = y * (scl + 1.f) + sh;
;         u32x2 pk; pk.x = cvt_pk_bf16(y[0], y[1]); pk.y = cvt_pk_bf16(y[2], y[3]);
;         *(u32x2*)(hb + (size_t)row * 1024 + col) = pk;
;       }
	v_pk_add_f32 v[54:55], v[64:65], 1.0 op_sel_hi:[1,0]
	v_pk_add_f32 v[56:57], v[62:63], 1.0 op_sel_hi:[1,0]
	v_lshlrev_b64 v[72:73], 11, v[34:35]
	v_pk_fma_f32 v[32:33], v[54:55], v[32:33], v[60:61]
	v_pk_fma_f32 v[30:31], v[56:57], v[30:31], v[58:59]
	v_lshl_add_u64 v[62:63], v[44:45], 0, v[72:73]
	v_cvt_pk_bf16_f32 v30, v30, v31
	v_cvt_pk_bf16_f32 v31, v32, v33
	global_store_dwordx2 v[62:63], v[30:31], off
	v_mov_b32_e32 v30, v80
	v_mov_b32_e32 v31, v81
	v_mov_b32_e32 v32, v82
	v_mov_b32_e32 v33, v83
	v_lshl_add_u64 v[54:55], v[68:69], 0, v[52:53]
	v_mov_b32_e32 v54, v84
	v_mov_b32_e32 v55, v85
	v_mov_b32_e32 v56, v86
	v_mov_b32_e32 v57, v87
	s_nop 0
	v_mov_b32_e32 v58, v88
	v_mov_b32_e32 v59, v89
	v_mov_b32_e32 v60, v90
	v_mov_b32_e32 v61, v91
	v_pk_mul_f32 v[28:29], v[28:29], v[66:67] op_sel_hi:[1,0]
	v_pk_mul_f32 v[26:27], v[26:27], v[66:67] op_sel_hi:[1,0]
	v_pk_mul_f32 v[24:25], v[24:25], v[66:67] op_sel_hi:[1,0]
	v_pk_mul_f32 v[22:23], v[22:23], v[66:67] op_sel_hi:[1,0]
	v_pk_mul_f32 v[20:21], v[20:21], v[66:67] op_sel_hi:[1,0]
	v_pk_mul_f32 v[18:19], v[18:19], v[66:67] op_sel_hi:[1,0]
	v_pk_mul_f32 v[26:27], v[30:31], v[26:27]
	v_pk_mul_f32 v[28:29], v[32:33], v[28:29]
	v_pk_add_f32 v[30:31], v[56:57], 1.0 op_sel_hi:[1,0]
	v_pk_add_f32 v[32:33], v[54:55], 1.0 op_sel_hi:[1,0]
	v_pk_fma_f32 v[28:29], v[30:31], v[28:29], v[60:61]
	v_pk_fma_f32 v[26:27], v[32:33], v[26:27], v[58:59]
	v_lshl_add_u64 v[30:31], v[68:69], 0, v[50:51]
	v_cvt_pk_bf16_f32 v26, v26, v27
	v_cvt_pk_bf16_f32 v27, v28, v29
	global_store_dwordx2 v[62:63], v[26:27], off offset:512
	v_mov_b32_e32 v26, v92
	v_mov_b32_e32 v27, v93
	v_mov_b32_e32 v28, v94
	v_mov_b32_e32 v29, v95
	s_nop 0
	v_mov_b32_e32 v30, v96
	v_mov_b32_e32 v31, v97
	v_mov_b32_e32 v32, v98
	v_mov_b32_e32 v33, v99
	s_nop 0
	v_mov_b32_e32 v54, v100
	v_mov_b32_e32 v55, v101
	v_mov_b32_e32 v56, v102
	v_mov_b32_e32 v57, v103
	v_pk_mul_f32 v[22:23], v[26:27], v[22:23]
	v_pk_mul_f32 v[24:25], v[28:29], v[24:25]
	v_pk_add_f32 v[26:27], v[32:33], 1.0 op_sel_hi:[1,0]
	v_pk_add_f32 v[28:29], v[30:31], 1.0 op_sel_hi:[1,0]
	v_pk_fma_f32 v[24:25], v[26:27], v[24:25], v[56:57]
	v_pk_fma_f32 v[22:23], v[28:29], v[22:23], v[54:55]
	v_lshl_add_u64 v[26:27], v[68:69], 0, v[48:49]
	v_cvt_pk_bf16_f32 v22, v22, v23
	v_cvt_pk_bf16_f32 v23, v24, v25
	global_store_dwordx2 v[62:63], v[22:23], off offset:1024
	v_mov_b32_e32 v22, v104
	v_mov_b32_e32 v23, v105
	v_mov_b32_e32 v24, v106
	v_mov_b32_e32 v25, v107
	s_nop 0
	v_mov_b32_e32 v26, v108
	v_mov_b32_e32 v27, v109
	v_mov_b32_e32 v28, v110
	v_mov_b32_e32 v29, v111
	s_nop 0
	v_mov_b32_e32 v30, v112
	v_mov_b32_e32 v31, v113
	v_mov_b32_e32 v32, v114
	v_mov_b32_e32 v33, v115
	v_pk_mul_f32 v[18:19], v[18:19], v[22:23]
	v_pk_mul_f32 v[20:21], v[20:21], v[24:25]
	v_pk_add_f32 v[22:23], v[28:29], 1.0 op_sel_hi:[1,0]
	v_pk_add_f32 v[24:25], v[26:27], 1.0 op_sel_hi:[1,0]
	v_pk_fma_f32 v[20:21], v[20:21], v[22:23], v[32:33]
	v_pk_fma_f32 v[18:19], v[18:19], v[24:25], v[30:31]
	s_nop 0
	v_cvt_pk_bf16_f32 v18, v18, v19
	v_cvt_pk_bf16_f32 v19, v20, v21
	global_store_dwordx2 v[62:63], v[18:19], off offset:1536
.LBB0_196:
	s_or_b64 exec, exec, s[46:47]
	s_and_saveexec_b64 s[40:41], s[42:43]
	s_cbranch_execz .LBB0_167
	s_waitcnt vmcnt(0)
	v_mov_b32_e32 v20, v11
	v_mov_b32_e32 v21, v15
	v_mov_b32_e32 v18, v10
	v_mov_b32_e32 v19, v14
	v_pk_mul_f32 v[20:21], v[20:21], v[20:21]
	v_mov_b32_e32 v22, v3
	v_pk_fma_f32 v[18:19], v[18:19], v[18:19], v[20:21]
	v_mov_b32_e32 v20, v12
	v_mov_b32_e32 v21, v16
	v_pk_fma_f32 v[18:19], v[20:21], v[20:21], v[18:19]
	v_mov_b32_e32 v20, v13
	v_mov_b32_e32 v21, v17
	v_mov_b32_e32 v23, v7
	v_pk_fma_f32 v[18:19], v[20:21], v[20:21], v[18:19]
	v_mov_b32_e32 v20, v2
	v_mov_b32_e32 v21, v6
	v_pk_mul_f32 v[22:23], v[22:23], v[22:23]
	v_add_u32_e32 v24, v41, v39
	v_pk_fma_f32 v[20:21], v[20:21], v[20:21], v[22:23]
	v_mov_b32_e32 v22, v4
	v_mov_b32_e32 v23, v8
	v_pk_fma_f32 v[20:21], v[22:23], v[22:23], v[20:21]
	v_mov_b32_e32 v22, v5
	v_mov_b32_e32 v23, v9
	v_mul_i32_i24_e32 v25, 0xfffff700, v24
	v_pk_fma_f32 v[30:31], v[22:23], v[22:23], v[20:21]
	v_add_f32_e32 v18, v18, v19
	v_add_f32_e32 v31, v31, v18
	v_add3_u32 v18, s86, v25, v34
	s_movk_i32 s18, 0xff
	v_cmp_lt_i32_e32 vcc, s18, v18
	s_mov_b64 s[18:19], 0x1000
	v_add_f32_e32 v30, v30, v31
	v_cndmask_b32_e32 v18, 8, v24, vcc
	v_mul_hi_i32_i24_e32 v19, 0x6000, v18
	v_mul_i32_i24_e32 v18, 0x6000, v18
	v_lshl_add_u64 v[22:23], s[26:27], 0, v[18:19]
	v_lshl_add_u64 v[32:33], v[22:23], 0, s[18:19]
	v_lshl_add_u64 v[54:55], v[22:23], 0, v[0:1]
	v_lshl_add_u64 v[26:27], v[32:33], 0, v[0:1]
	global_load_dwordx4 v[18:21], v[36:37], off
	global_load_dwordx4 v[22:25], v[54:55], off
	s_nop 0
	global_load_dwordx4 v[26:29], v[26:27], off
	global_load_dwordx4 v[80:83], v[36:37], off offset:1024
	v_mov_b32_e32 v53, v1
	v_lshl_add_u64 v[116:117], v[32:33], 0, v[52:53]
	global_load_dwordx4 v[84:87], v[116:117], off
	global_load_dwordx4 v[88:91], v[54:55], off offset:1024
	global_load_dwordx4 v[92:95], v[36:37], off offset:2048
	v_mov_b32_e32 v51, v1
	v_lshl_add_u64 v[118:119], v[32:33], 0, v[50:51]
	global_load_dwordx4 v[96:99], v[118:119], off
	global_load_dwordx4 v[100:103], v[54:55], off offset:2048
	global_load_dwordx4 v[104:107], v[36:37], off offset:3072
	v_mov_b32_e32 v49, v1
	v_lshl_add_u64 v[120:121], v[32:33], 0, v[48:49]
	global_load_dwordx4 v[108:111], v[120:121], off
	global_load_dwordx4 v[112:115], v[54:55], off offset:3072
	v_and_b32_e32 v31, 64, v192
	v_add_u32_e32 v31, 64, v31
	v_xor_b32_e32 v35, 32, v192
	v_cmp_lt_i32_e32 vcc, v35, v31
	v_ashrrev_i32_e32 v47, 31, v46
	v_lshlrev_b64 v[46:47], 11, v[46:47]
	v_cndmask_b32_e32 v35, v192, v35, vcc
	v_lshlrev_b32_e32 v35, 2, v35
	ds_bpermute_b32 v35, v35, v30
	v_mov_b32_e32 v53, v1
	v_mov_b32_e32 v51, v1
	v_mov_b32_e32 v49, v1
	s_waitcnt lgkmcnt(0)
; DI unsigned cvt_pk_bf16(float lo, float hi) { f32x2_t v = {lo, hi}; bf16x2_t b = __builtin_convertvector(v, bf16x2_t); return __builtin_bit_cast(unsigned, b); }
; DI void phase_norm(const Params& p, int l, const float* g, int shift_idx, bool skip_ctx, bool from_input) {
;     ...
;       ss = wave_sum(ss);
;       const float rs = rsqrtf(ss * (1.f / 1024.f) + EPS);
;       const float* mr = mod + (size_t)(t < CTXL ? 8 : b) * 6144 + shift_idx * 1024;
; #pragma unroll
;       for (int i = 0; i < 4; ++i) {
;         const int col = lane * 4 + i * 256;
;         const f32x4 gg = *(const f32x4*)(g + col), sh = *(const f32x4*)(mr + col), scl = *(const f32x4*)(mr + 1024 + col);
;         f32x4 y = (v[u][i] * rs) * gg;
;         y = y * (scl + 1.f) + sh;
;         u32x2 pk; pk.x = cvt_pk_bf16(y[0], y[1]); pk.y = cvt_pk_bf16(y[2], y[3]);
;         *(u32x2*)(hb + (size_t)row * 1024 + col) = pk;
;       }
	v_add_f32_e32 v30, v30, v35
	v_xor_b32_e32 v35, 16, v192
	v_cmp_lt_i32_e32 vcc, v35, v31
	s_nop 1
	v_cndmask_b32_e32 v35, v192, v35, vcc
	v_lshlrev_b32_e32 v35, 2, v35
	ds_bpermute_b32 v35, v35, v30
	s_waitcnt lgkmcnt(0)
	v_add_f32_e32 v30, v30, v35
	v_xor_b32_e32 v35, 8, v192
	v_cmp_lt_i32_e32 vcc, v35, v31
	s_nop 1
	v_cndmask_b32_e32 v35, v192, v35, vcc
	v_lshlrev_b32_e32 v35, 2, v35
	ds_bpermute_b32 v35, v35, v30
	s_waitcnt lgkmcnt(0)
	v_add_f32_e32 v30, v30, v35
	v_xor_b32_e32 v35, 4, v192
	v_cmp_lt_i32_e32 vcc, v35, v31
	s_nop 1
	v_cndmask_b32_e32 v35, v192, v35, vcc
	v_lshlrev_b32_e32 v35, 2, v35
	ds_bpermute_b32 v35, v35, v30
	s_waitcnt lgkmcnt(0)
	v_add_f32_e32 v30, v30, v35
	v_xor_b32_e32 v35, 2, v192
	v_cmp_lt_i32_e32 vcc, v35, v31
	s_nop 1
	v_cndmask_b32_e32 v35, v192, v35, vcc
	v_lshlrev_b32_e32 v35, 2, v35
	ds_bpermute_b32 v35, v35, v30
	s_waitcnt lgkmcnt(0)
	v_add_f32_e32 v30, v30, v35
	v_xor_b32_e32 v35, 1, v192
	v_cmp_lt_i32_e32 vcc, v35, v31
	s_nop 1
	v_cndmask_b32_e32 v31, v192, v35, vcc
	v_lshlrev_b32_e32 v31, 2, v31
	ds_bpermute_b32 v31, v31, v30
	s_waitcnt lgkmcnt(0)
	v_add_f32_e32 v30, v30, v31
	v_fmamk_f32 v30, v30, 0x3a800000, v148
	v_mul_f32_e32 v31, 0x4b800000, v30
	v_cmp_gt_f32_e32 vcc, s2, v30
	s_nop 1
	v_cndmask_b32_e32 v30, v30, v31, vcc
	v_rsq_f32_e32 v30, v30
	s_nop 0
	v_mul_f32_e32 v31, 0x45800000, v30
	v_cndmask_b32_e32 v30, v30, v31, vcc
	v_pk_mul_f32 v[16:17], v[16:17], v[30:31] op_sel_hi:[1,0]
	v_pk_mul_f32 v[14:15], v[14:15], v[30:31] op_sel_hi:[1,0]
	s_waitcnt vmcnt(2)
	v_pk_mul_f32 v[16:17], v[20:21], v[16:17]
	v_pk_mul_f32 v[14:15], v[18:19], v[14:15]
	s_waitcnt vmcnt(0)
	v_pk_add_f32 v[18:19], v[28:29], 1.0 op_sel_hi:[1,0]
	v_pk_add_f32 v[20:21], v[26:27], 1.0 op_sel_hi:[1,0]
	v_pk_fma_f32 v[16:17], v[18:19], v[16:17], v[24:25]
	v_pk_fma_f32 v[14:15], v[20:21], v[14:15], v[22:23]
	v_lshl_add_u64 v[26:27], v[44:45], 0, v[46:47]
	v_cvt_pk_bf16_f32 v14, v14, v15
	v_cvt_pk_bf16_f32 v15, v16, v17
	global_store_dwordx2 v[26:27], v[14:15], off
	v_mov_b32_e32 v14, v80
	v_mov_b32_e32 v15, v81
	v_mov_b32_e32 v16, v82
	v_mov_b32_e32 v17, v83
	v_lshl_add_u64 v[18:19], v[32:33], 0, v[52:53]
	v_mov_b32_e32 v18, v84
	v_mov_b32_e32 v19, v85
	v_mov_b32_e32 v20, v86
	v_mov_b32_e32 v21, v87
	s_nop 0
	v_mov_b32_e32 v22, v88
	v_mov_b32_e32 v23, v89
	v_mov_b32_e32 v24, v90
	v_mov_b32_e32 v25, v91
	v_pk_mul_f32 v[12:13], v[12:13], v[30:31] op_sel_hi:[1,0]
	v_pk_mul_f32 v[10:11], v[10:11], v[30:31] op_sel_hi:[1,0]
	v_pk_mul_f32 v[8:9], v[8:9], v[30:31] op_sel_hi:[1,0]
	v_pk_mul_f32 v[6:7], v[6:7], v[30:31] op_sel_hi:[1,0]
	v_pk_mul_f32 v[4:5], v[4:5], v[30:31] op_sel_hi:[1,0]
	v_pk_mul_f32 v[2:3], v[2:3], v[30:31] op_sel_hi:[1,0]
	v_pk_mul_f32 v[10:11], v[14:15], v[10:11]
	v_pk_mul_f32 v[12:13], v[16:17], v[12:13]
	v_pk_add_f32 v[14:15], v[20:21], 1.0 op_sel_hi:[1,0]
	v_pk_add_f32 v[16:17], v[18:19], 1.0 op_sel_hi:[1,0]
	v_pk_fma_f32 v[12:13], v[14:15], v[12:13], v[24:25]
	v_pk_fma_f32 v[10:11], v[16:17], v[10:11], v[22:23]
	v_lshl_add_u64 v[14:15], v[32:33], 0, v[50:51]
	v_cvt_pk_bf16_f32 v10, v10, v11
	v_cvt_pk_bf16_f32 v11, v12, v13
	global_store_dwordx2 v[26:27], v[10:11], off offset:512
	v_mov_b32_e32 v10, v92
	v_mov_b32_e32 v11, v93
	v_mov_b32_e32 v12, v94
	v_mov_b32_e32 v13, v95
	s_nop 0
	v_mov_b32_e32 v14, v96
	v_mov_b32_e32 v15, v97
	v_mov_b32_e32 v16, v98
	v_mov_b32_e32 v17, v99
	s_nop 0
	v_mov_b32_e32 v18, v100
	v_mov_b32_e32 v19, v101
	v_mov_b32_e32 v20, v102
	v_mov_b32_e32 v21, v103
	v_pk_mul_f32 v[6:7], v[10:11], v[6:7]
	v_pk_mul_f32 v[8:9], v[12:13], v[8:9]
	v_pk_add_f32 v[10:11], v[16:17], 1.0 op_sel_hi:[1,0]
	v_pk_add_f32 v[12:13], v[14:15], 1.0 op_sel_hi:[1,0]
	v_pk_fma_f32 v[8:9], v[10:11], v[8:9], v[20:21]
	v_pk_fma_f32 v[6:7], v[12:13], v[6:7], v[18:19]
	v_lshl_add_u64 v[10:11], v[32:33], 0, v[48:49]
	v_cvt_pk_bf16_f32 v6, v6, v7
	v_cvt_pk_bf16_f32 v7, v8, v9
	global_store_dwordx2 v[26:27], v[6:7], off offset:1024
	v_mov_b32_e32 v6, v104
	v_mov_b32_e32 v7, v105
	v_mov_b32_e32 v8, v106
	v_mov_b32_e32 v9, v107
	s_nop 0
	v_mov_b32_e32 v10, v108
	v_mov_b32_e32 v11, v109
	v_mov_b32_e32 v12, v110
	v_mov_b32_e32 v13, v111
	s_nop 0
	v_mov_b32_e32 v14, v112
	v_mov_b32_e32 v15, v113
	v_mov_b32_e32 v16, v114
	v_mov_b32_e32 v17, v115
	v_pk_mul_f32 v[2:3], v[2:3], v[6:7]
	v_pk_mul_f32 v[4:5], v[4:5], v[8:9]
	v_pk_add_f32 v[6:7], v[12:13], 1.0 op_sel_hi:[1,0]
	v_pk_add_f32 v[8:9], v[10:11], 1.0 op_sel_hi:[1,0]
	v_pk_fma_f32 v[4:5], v[4:5], v[6:7], v[16:17]
	v_pk_fma_f32 v[2:3], v[2:3], v[8:9], v[14:15]
	s_nop 0
	v_cvt_pk_bf16_f32 v2, v2, v3
	v_cvt_pk_bf16_f32 v3, v4, v5
	global_store_dwordx2 v[26:27], v[2:3], off offset:1536
	s_branch .LBB0_167

; DI unsigned cvt_pk_bf16(float lo, float hi) { f32x2_t v = {lo, hi}; bf16x2_t b = __builtin_convertvector(v, bf16x2_t); return __builtin_bit_cast(unsigned, b); }
; DI void phase_norm(const Params& p, int l, const float* g, int shift_idx, bool skip_ctx, bool from_input) {
;     ...
;       float ss = 0.f;
; #pragma unroll
;       for (int i = 0; i < 4; ++i) ss += v[u][i][0] * v[u][i][0] + v[u][i][1] * v[u][i][1] + v[u][i][2] * v[u][i][2] + v[u][i][3] * v[u][i][3];
;       ss = wave_sum(ss);
;       const float rs = rsqrtf(ss * (1.f / 1024.f) + EPS);
;       const float* mr = mod + (size_t)(t < CTXL ? 8 : b) * 6144 + shift_idx * 1024;
; #pragma unroll
;       for (int i = 0; i < 4; ++i) {
;         const int col = lane * 4 + i * 256;
;         const f32x4 gg = *(const f32x4*)(g + col), sh = *(const f32x4*)(mr + col), scl = *(const f32x4*)(mr + 1024 + col);
;         f32x4 y = (v[u][i] * rs) * gg;
;         y = y * (scl + 1.f) + sh;
;         u32x2 pk; pk.x = cvt_pk_bf16(y[0], y[1]); pk.y = cvt_pk_bf16(y[2], y[3]);
;         *(u32x2*)(hb + (size_t)row * 1024 + col) = pk;
;       }
.LBB0_1487:
	s_or_b64 exec, exec, s[42:43]
	v_lshlrev_b32_e32 v0, 2, v40
	v_lshlrev_b32_e32 v56, 2, v44
	v_lshlrev_b32_e32 v54, 2, v46
	v_lshlrev_b32_e32 v52, 2, v48
	s_and_saveexec_b64 s[42:43], s[44:45]
	s_cbranch_execz .LBB0_1489
	s_waitcnt vmcnt(0)
	v_mov_b32_e32 v60, v27
	v_mov_b32_e32 v61, v31
	v_mov_b32_e32 v36, v26
	v_mov_b32_e32 v37, v30
	v_pk_mul_f32 v[60:61], v[60:61], v[60:61]
	v_mov_b32_e32 v62, v19
	v_pk_fma_f32 v[36:37], v[36:37], v[36:37], v[60:61]
	v_mov_b32_e32 v60, v28
	v_mov_b32_e32 v61, v32
	v_pk_fma_f32 v[36:37], v[60:61], v[60:61], v[36:37]
	v_mov_b32_e32 v60, v29
	v_mov_b32_e32 v61, v33
	v_mov_b32_e32 v63, v23
	v_pk_fma_f32 v[36:37], v[60:61], v[60:61], v[36:37]
	v_mov_b32_e32 v60, v18
	v_mov_b32_e32 v61, v22
	v_pk_mul_f32 v[62:63], v[62:63], v[62:63]
	v_add_f32_e32 v36, v36, v37
	v_pk_fma_f32 v[60:61], v[60:61], v[60:61], v[62:63]
	v_mov_b32_e32 v62, v20
	v_mov_b32_e32 v63, v24
	v_pk_fma_f32 v[60:61], v[62:63], v[62:63], v[60:61]
	v_mov_b32_e32 v62, v21
	v_mov_b32_e32 v63, v25
	v_pk_fma_f32 v[60:61], v[62:63], v[62:63], v[60:61]
	s_movk_i32 s18, 0xff
	v_add_f32_e32 v36, v61, v36
	v_add_f32_e32 v36, v60, v36
	ds_bpermute_b32 v37, v197, v36
	v_ashrrev_i32_e32 v39, 31, v38
	v_lshlrev_b64 v[76:77], 11, v[38:39]
	v_mov_b32_e32 v57, v1
	v_mov_b32_e32 v55, v1
	s_waitcnt lgkmcnt(0)
	v_add_f32_e32 v36, v36, v37
	ds_bpermute_b32 v37, v198, v36
	v_mov_b32_e32 v53, v1
	s_waitcnt lgkmcnt(0)
	v_add_f32_e32 v36, v36, v37
	ds_bpermute_b32 v37, v199, v36
	s_waitcnt lgkmcnt(0)
	v_add_f32_e32 v36, v36, v37
	ds_bpermute_b32 v37, v200, v36
	s_waitcnt lgkmcnt(0)
	v_add_f32_e32 v36, v36, v37
	ds_bpermute_b32 v37, v201, v36
	s_waitcnt lgkmcnt(0)
	v_add_f32_e32 v36, v36, v37
	ds_bpermute_b32 v37, v202, v36
	s_waitcnt lgkmcnt(0)
	v_add_f32_e32 v36, v36, v37
	v_fmamk_f32 v36, v36, 0x3a800000, v148
	v_cmp_gt_f32_e32 vcc, s2, v36
	v_mul_f32_e32 v37, 0x4b800000, v36
	s_nop 0
	v_cndmask_b32_e32 v36, v36, v37, vcc
	v_rsq_f32_e32 v36, v36
	s_nop 0
	v_mul_f32_e32 v37, 0x45800000, v36
	v_cndmask_b32_e32 v60, v36, v37, vcc
	v_cmp_lt_i32_e32 vcc, s18, v35
	s_mov_b64 s[18:19], 0x1000
	v_pk_mul_f32 v[32:33], v[32:33], v[60:61] op_sel_hi:[1,0]
	v_cndmask_b32_e32 v34, 8, v34, vcc
	v_mul_hi_i32_i24_e32 v35, 0x6000, v34
	v_mul_i32_i24_e32 v34, 0x6000, v34
	v_lshl_add_u64 v[64:65], s[4:5], 0, v[34:35]
	v_lshl_add_u64 v[62:63], v[64:65], 0, s[18:19]
	v_lshl_add_u64 v[66:67], v[64:65], 0, v[0:1]
	v_lshl_add_u64 v[64:65], v[62:63], 0, v[0:1]
	global_load_dwordx4 v[34:37], v[42:43], off
	global_load_dwordx4 v[68:71], v[66:67], off
	global_load_dwordx4 v[72:75], v[64:65], off
	global_load_dwordx4 v[80:83], v[42:43], off offset:1024
	global_load_dwordx4 v[84:87], v[66:67], off offset:1024
	v_mov_b32_e32 v57, v1
	v_lshl_add_u64 v[116:117], v[62:63], 0, v[56:57]
	global_load_dwordx4 v[88:91], v[116:117], off
	global_load_dwordx4 v[92:95], v[42:43], off offset:2048
	global_load_dwordx4 v[96:99], v[66:67], off offset:2048
	v_mov_b32_e32 v55, v1
	v_lshl_add_u64 v[118:119], v[62:63], 0, v[54:55]
	global_load_dwordx4 v[100:103], v[118:119], off
	global_load_dwordx4 v[104:107], v[42:43], off offset:3072
	global_load_dwordx4 v[108:111], v[66:67], off offset:3072
	v_mov_b32_e32 v53, v1
	v_lshl_add_u64 v[120:121], v[62:63], 0, v[52:53]
	global_load_dwordx4 v[112:115], v[120:121], off
	v_pk_mul_f32 v[30:31], v[30:31], v[60:61] op_sel_hi:[1,0]
	v_lshl_add_u64 v[64:65], v[50:51], 0, v[76:77]
	v_pk_mul_f32 v[28:29], v[28:29], v[60:61] op_sel_hi:[1,0]
	v_pk_mul_f32 v[26:27], v[26:27], v[60:61] op_sel_hi:[1,0]
	v_pk_mul_f32 v[24:25], v[24:25], v[60:61] op_sel_hi:[1,0]
	v_pk_mul_f32 v[22:23], v[22:23], v[60:61] op_sel_hi:[1,0]
	v_pk_mul_f32 v[20:21], v[20:21], v[60:61] op_sel_hi:[1,0]
	v_pk_mul_f32 v[18:19], v[18:19], v[60:61] op_sel_hi:[1,0]
	s_waitcnt vmcnt(2)
	v_pk_mul_f32 v[30:31], v[34:35], v[30:31]
	v_pk_mul_f32 v[32:33], v[36:37], v[32:33]
	s_waitcnt vmcnt(0)
	v_pk_add_f32 v[34:35], v[74:75], 1.0 op_sel_hi:[1,0]
	v_pk_add_f32 v[36:37], v[72:73], 1.0 op_sel_hi:[1,0]
	v_pk_fma_f32 v[32:33], v[34:35], v[32:33], v[70:71]
	v_pk_fma_f32 v[30:31], v[36:37], v[30:31], v[68:69]
	v_lshl_add_u64 v[68:69], v[62:63], 0, v[56:57]
	v_cvt_pk_bf16_f32 v30, v30, v31
	v_cvt_pk_bf16_f32 v31, v32, v33
	global_store_dwordx2 v[64:65], v[30:31], off
	v_mov_b32_e32 v34, v80
	v_mov_b32_e32 v35, v81
	v_mov_b32_e32 v36, v82
	v_mov_b32_e32 v37, v83
	s_nop 0
	v_mov_b32_e32 v30, v84
	v_mov_b32_e32 v31, v85
	v_mov_b32_e32 v32, v86
	v_mov_b32_e32 v33, v87
	v_pk_mul_f32 v[26:27], v[34:35], v[26:27]
	v_mov_b32_e32 v68, v88
	v_mov_b32_e32 v69, v89
	v_mov_b32_e32 v70, v90
	v_mov_b32_e32 v71, v91
	v_pk_mul_f32 v[28:29], v[36:37], v[28:29]
	v_pk_add_f32 v[34:35], v[70:71], 1.0 op_sel_hi:[1,0]
	v_pk_add_f32 v[36:37], v[68:69], 1.0 op_sel_hi:[1,0]
	v_pk_fma_f32 v[28:29], v[34:35], v[28:29], v[32:33]
	v_pk_fma_f32 v[26:27], v[36:37], v[26:27], v[30:31]
	v_lshl_add_u64 v[34:35], v[62:63], 0, v[54:55]
	v_cvt_pk_bf16_f32 v26, v26, v27
	v_cvt_pk_bf16_f32 v27, v28, v29
	global_store_dwordx2 v[64:65], v[26:27], off offset:512
	v_mov_b32_e32 v26, v92
	v_mov_b32_e32 v27, v93
	v_mov_b32_e32 v28, v94
	v_mov_b32_e32 v29, v95
	s_nop 0
	v_mov_b32_e32 v30, v96
	v_mov_b32_e32 v31, v97
	v_mov_b32_e32 v32, v98
	v_mov_b32_e32 v33, v99
	v_pk_mul_f32 v[22:23], v[26:27], v[22:23]
	v_mov_b32_e32 v34, v100
	v_mov_b32_e32 v35, v101
	v_mov_b32_e32 v36, v102
	v_mov_b32_e32 v37, v103
	v_pk_mul_f32 v[24:25], v[28:29], v[24:25]
	v_pk_add_f32 v[26:27], v[36:37], 1.0 op_sel_hi:[1,0]
	v_pk_add_f32 v[28:29], v[34:35], 1.0 op_sel_hi:[1,0]
	v_pk_fma_f32 v[24:25], v[26:27], v[24:25], v[32:33]
	v_pk_fma_f32 v[22:23], v[28:29], v[22:23], v[30:31]
	v_lshl_add_u64 v[30:31], v[62:63], 0, v[52:53]
	v_cvt_pk_bf16_f32 v22, v22, v23
	v_cvt_pk_bf16_f32 v23, v24, v25
	global_store_dwordx2 v[64:65], v[22:23], off offset:1024
	v_mov_b32_e32 v22, v104
	v_mov_b32_e32 v23, v105
	v_mov_b32_e32 v24, v106
	v_mov_b32_e32 v25, v107
	s_nop 0
	v_mov_b32_e32 v26, v108
	v_mov_b32_e32 v27, v109
	v_mov_b32_e32 v28, v110
	v_mov_b32_e32 v29, v111
	v_pk_mul_f32 v[18:19], v[18:19], v[22:23]
	v_mov_b32_e32 v30, v112
	v_mov_b32_e32 v31, v113
	v_mov_b32_e32 v32, v114
	v_mov_b32_e32 v33, v115
	v_pk_mul_f32 v[20:21], v[20:21], v[24:25]
	v_pk_add_f32 v[22:23], v[32:33], 1.0 op_sel_hi:[1,0]
	v_pk_add_f32 v[24:25], v[30:31], 1.0 op_sel_hi:[1,0]
	v_pk_fma_f32 v[20:21], v[20:21], v[22:23], v[28:29]
	v_pk_fma_f32 v[18:19], v[18:19], v[24:25], v[26:27]
	s_nop 0
	v_cvt_pk_bf16_f32 v18, v18, v19
	v_cvt_pk_bf16_f32 v19, v20, v21
	global_store_dwordx2 v[64:65], v[18:19], off offset:1536
; DI unsigned cvt_pk_bf16(float lo, float hi) { f32x2_t v = {lo, hi}; bf16x2_t b = __builtin_convertvector(v, bf16x2_t); return __builtin_bit_cast(unsigned, b); }
; DI void phase_norm(const Params& p, int l, const float* g, int shift_idx, bool skip_ctx, bool from_input) {
;     ...
;       float ss = 0.f;
; #pragma unroll
;       for (int i = 0; i < 4; ++i) ss += v[u][i][0] * v[u][i][0] + v[u][i][1] * v[u][i][1] + v[u][i][2] * v[u][i][2] + v[u][i][3] * v[u][i][3];
;       ss = wave_sum(ss);
;       const float rs = rsqrtf(ss * (1.f / 1024.f) + EPS);
;       const float* mr = mod + (size_t)(t < CTXL ? 8 : b) * 6144 + shift_idx * 1024;
; #pragma unroll
;       for (int i = 0; i < 4; ++i) {
;         const int col = lane * 4 + i * 256;
;         const f32x4 gg = *(const f32x4*)(g + col), sh = *(const f32x4*)(mr + col), scl = *(const f32x4*)(mr + 1024 + col);
;         f32x4 y = (v[u][i] * rs) * gg;
;         y = y * (scl + 1.f) + sh;
;         u32x2 pk; pk.x = cvt_pk_bf16(y[0], y[1]); pk.y = cvt_pk_bf16(y[2], y[3]);
;         *(u32x2*)(hb + (size_t)row * 1024 + col) = pk;
;       }
.LBB0_1489:
	s_or_b64 exec, exec, s[42:43]
	s_and_saveexec_b64 s[42:43], s[40:41]
	s_cbranch_execz .LBB0_1470
	s_waitcnt vmcnt(0)
	v_mov_b32_e32 v20, v11
	v_mov_b32_e32 v21, v15
	v_mov_b32_e32 v18, v10
	v_mov_b32_e32 v19, v14
	v_pk_mul_f32 v[20:21], v[20:21], v[20:21]
	v_mov_b32_e32 v22, v3
	v_pk_fma_f32 v[18:19], v[18:19], v[18:19], v[20:21]
	v_mov_b32_e32 v20, v12
	v_mov_b32_e32 v21, v16
	v_pk_fma_f32 v[18:19], v[20:21], v[20:21], v[18:19]
	v_mov_b32_e32 v20, v13
	v_mov_b32_e32 v21, v17
	v_mov_b32_e32 v23, v7
	v_pk_fma_f32 v[18:19], v[20:21], v[20:21], v[18:19]
	v_mov_b32_e32 v20, v2
	v_mov_b32_e32 v21, v6
	v_pk_mul_f32 v[22:23], v[22:23], v[22:23]
	v_add_f32_e32 v18, v18, v19
	v_pk_fma_f32 v[20:21], v[20:21], v[20:21], v[22:23]
	v_mov_b32_e32 v22, v4
	v_mov_b32_e32 v23, v8
	v_pk_fma_f32 v[20:21], v[22:23], v[22:23], v[20:21]
	v_mov_b32_e32 v22, v5
	v_mov_b32_e32 v23, v9
	v_pk_fma_f32 v[20:21], v[22:23], v[22:23], v[20:21]
	v_add_u32_e32 v24, v45, v41
	v_add_f32_e32 v18, v21, v18
	v_add_f32_e32 v18, v20, v18
	ds_bpermute_b32 v20, v197, v18
	v_mul_i32_i24_e32 v25, 0xfffff700, v24
	v_add3_u32 v19, s86, v25, v38
	s_movk_i32 s18, 0xff
	v_ashrrev_i32_e32 v59, 31, v58
	s_waitcnt lgkmcnt(0)
	v_add_f32_e32 v18, v18, v20
	ds_bpermute_b32 v20, v198, v18
	v_lshlrev_b64 v[58:59], 11, v[58:59]
	v_mov_b32_e32 v57, v1
	v_mov_b32_e32 v55, v1
	v_mov_b32_e32 v53, v1
	s_waitcnt lgkmcnt(0)
	v_add_f32_e32 v18, v18, v20
	ds_bpermute_b32 v20, v199, v18
	s_waitcnt lgkmcnt(0)
	v_add_f32_e32 v18, v18, v20
	ds_bpermute_b32 v20, v200, v18
	s_waitcnt lgkmcnt(0)
	v_add_f32_e32 v18, v18, v20
	ds_bpermute_b32 v20, v201, v18
	s_waitcnt lgkmcnt(0)
	v_add_f32_e32 v18, v18, v20
	ds_bpermute_b32 v20, v202, v18
	s_waitcnt lgkmcnt(0)
	v_add_f32_e32 v18, v18, v20
	v_fmamk_f32 v18, v18, 0x3a800000, v148
	v_cmp_gt_f32_e32 vcc, s2, v18
	v_mul_f32_e32 v20, 0x4b800000, v18
	s_nop 0
	v_cndmask_b32_e32 v18, v18, v20, vcc
	v_rsq_f32_e32 v18, v18
	s_nop 0
	v_mul_f32_e32 v20, 0x45800000, v18
	v_cndmask_b32_e32 v22, v18, v20, vcc
	v_cmp_lt_i32_e32 vcc, s18, v19
	s_mov_b64 s[18:19], 0x1000
	v_pk_mul_f32 v[16:17], v[16:17], v[22:23] op_sel_hi:[1,0]
	v_cndmask_b32_e32 v18, 8, v24, vcc
	v_mul_hi_i32_i24_e32 v19, 0x6000, v18
	v_mul_i32_i24_e32 v18, 0x6000, v18
	v_lshl_add_u64 v[26:27], s[4:5], 0, v[18:19]
	v_lshl_add_u64 v[24:25], v[26:27], 0, s[18:19]
	v_lshl_add_u64 v[28:29], v[26:27], 0, v[0:1]
	v_lshl_add_u64 v[26:27], v[24:25], 0, v[0:1]
	global_load_dwordx4 v[18:21], v[42:43], off
	global_load_dwordx4 v[30:33], v[28:29], off
	global_load_dwordx4 v[34:37], v[26:27], off
	global_load_dwordx4 v[80:83], v[42:43], off offset:1024
	global_load_dwordx4 v[84:87], v[28:29], off offset:1024
	v_mov_b32_e32 v57, v1
	v_lshl_add_u64 v[116:117], v[24:25], 0, v[56:57]
	global_load_dwordx4 v[88:91], v[116:117], off
	global_load_dwordx4 v[92:95], v[42:43], off offset:2048
	global_load_dwordx4 v[96:99], v[28:29], off offset:2048
	v_mov_b32_e32 v55, v1
	v_lshl_add_u64 v[118:119], v[24:25], 0, v[54:55]
	global_load_dwordx4 v[100:103], v[118:119], off
	global_load_dwordx4 v[104:107], v[42:43], off offset:3072
	global_load_dwordx4 v[108:111], v[28:29], off offset:3072
	v_mov_b32_e32 v53, v1
	v_lshl_add_u64 v[120:121], v[24:25], 0, v[52:53]
	global_load_dwordx4 v[112:115], v[120:121], off
	v_pk_mul_f32 v[14:15], v[14:15], v[22:23] op_sel_hi:[1,0]
	v_lshl_add_u64 v[26:27], v[50:51], 0, v[58:59]
	v_pk_mul_f32 v[12:13], v[12:13], v[22:23] op_sel_hi:[1,0]
	v_pk_mul_f32 v[10:11], v[10:11], v[22:23] op_sel_hi:[1,0]
	v_pk_mul_f32 v[8:9], v[8:9], v[22:23] op_sel_hi:[1,0]
	v_pk_mul_f32 v[6:7], v[6:7], v[22:23] op_sel_hi:[1,0]
	v_pk_mul_f32 v[4:5], v[4:5], v[22:23] op_sel_hi:[1,0]
	v_pk_mul_f32 v[2:3], v[2:3], v[22:23] op_sel_hi:[1,0]
	s_waitcnt vmcnt(2)
	v_pk_mul_f32 v[14:15], v[18:19], v[14:15]
	v_pk_mul_f32 v[16:17], v[20:21], v[16:17]
	s_waitcnt vmcnt(0)
	v_pk_add_f32 v[18:19], v[36:37], 1.0 op_sel_hi:[1,0]
	v_pk_add_f32 v[20:21], v[34:35], 1.0 op_sel_hi:[1,0]
	v_pk_fma_f32 v[16:17], v[18:19], v[16:17], v[32:33]
	v_pk_fma_f32 v[14:15], v[20:21], v[14:15], v[30:31]
	v_lshl_add_u64 v[30:31], v[24:25], 0, v[56:57]
	v_cvt_pk_bf16_f32 v14, v14, v15
	v_cvt_pk_bf16_f32 v15, v16, v17
	global_store_dwordx2 v[26:27], v[14:15], off
	v_mov_b32_e32 v18, v80
	v_mov_b32_e32 v19, v81
	v_mov_b32_e32 v20, v82
	v_mov_b32_e32 v21, v83
	s_nop 0
	v_mov_b32_e32 v14, v84
	v_mov_b32_e32 v15, v85
	v_mov_b32_e32 v16, v86
	v_mov_b32_e32 v17, v87
	v_pk_mul_f32 v[10:11], v[18:19], v[10:11]
	v_mov_b32_e32 v30, v88
	v_mov_b32_e32 v31, v89
	v_mov_b32_e32 v32, v90
	v_mov_b32_e32 v33, v91
	v_pk_mul_f32 v[12:13], v[20:21], v[12:13]
	v_pk_add_f32 v[18:19], v[32:33], 1.0 op_sel_hi:[1,0]
	v_pk_add_f32 v[20:21], v[30:31], 1.0 op_sel_hi:[1,0]
	v_pk_fma_f32 v[12:13], v[18:19], v[12:13], v[16:17]
	v_pk_fma_f32 v[10:11], v[20:21], v[10:11], v[14:15]
	v_lshl_add_u64 v[18:19], v[24:25], 0, v[54:55]
	v_cvt_pk_bf16_f32 v10, v10, v11
	v_cvt_pk_bf16_f32 v11, v12, v13
	global_store_dwordx2 v[26:27], v[10:11], off offset:512
	v_mov_b32_e32 v10, v92
	v_mov_b32_e32 v11, v93
	v_mov_b32_e32 v12, v94
	v_mov_b32_e32 v13, v95
	s_nop 0
	v_mov_b32_e32 v14, v96
	v_mov_b32_e32 v15, v97
	v_mov_b32_e32 v16, v98
	v_mov_b32_e32 v17, v99
	v_pk_mul_f32 v[6:7], v[10:11], v[6:7]
	v_mov_b32_e32 v18, v100
	v_mov_b32_e32 v19, v101
	v_mov_b32_e32 v20, v102
	v_mov_b32_e32 v21, v103
	v_pk_mul_f32 v[8:9], v[12:13], v[8:9]
	v_pk_add_f32 v[10:11], v[20:21], 1.0 op_sel_hi:[1,0]
	v_pk_add_f32 v[12:13], v[18:19], 1.0 op_sel_hi:[1,0]
	v_pk_fma_f32 v[8:9], v[10:11], v[8:9], v[16:17]
	v_pk_fma_f32 v[6:7], v[12:13], v[6:7], v[14:15]
	v_lshl_add_u64 v[14:15], v[24:25], 0, v[52:53]
	v_cvt_pk_bf16_f32 v6, v6, v7
	v_cvt_pk_bf16_f32 v7, v8, v9
	global_store_dwordx2 v[26:27], v[6:7], off offset:1024
	v_mov_b32_e32 v6, v104
	v_mov_b32_e32 v7, v105
	v_mov_b32_e32 v8, v106
	v_mov_b32_e32 v9, v107
	s_nop 0
	v_mov_b32_e32 v10, v108
	v_mov_b32_e32 v11, v109
	v_mov_b32_e32 v12, v110
	v_mov_b32_e32 v13, v111
	v_pk_mul_f32 v[2:3], v[2:3], v[6:7]
	v_mov_b32_e32 v14, v112
	v_mov_b32_e32 v15, v113
	v_mov_b32_e32 v16, v114
	v_mov_b32_e32 v17, v115
	v_pk_mul_f32 v[4:5], v[4:5], v[8:9]
	v_pk_add_f32 v[6:7], v[16:17], 1.0 op_sel_hi:[1,0]
	v_pk_add_f32 v[8:9], v[14:15], 1.0 op_sel_hi:[1,0]
	v_pk_fma_f32 v[4:5], v[4:5], v[6:7], v[12:13]
	v_pk_fma_f32 v[2:3], v[2:3], v[8:9], v[10:11]
	s_nop 0
	v_cvt_pk_bf16_f32 v2, v2, v3
	v_cvt_pk_bf16_f32 v3, v4, v5
	global_store_dwordx2 v[26:27], v[2:3], off offset:1536
	s_branch .LBB0_1470
